# post_even loop: the vmcnt(0) that drained the just-issued next-row prefetch moved to the loop latch as vmcnt(2); invariant gains waited once before the loop
# baseline (speedup 1.0000x reference)
.LBB0_393:
	s_or_b64 exec, exec, s[30:31]
	v_readlane_b32 s0, v251, 63
	v_readlane_b32 s1, v252, 0
	s_andn2_b64 vcc, exec, s[0:1]
	s_waitcnt lgkmcnt(0)
	s_barrier
	s_cbranch_vccnz .LBB0_416
	v_and_b32_e32 v64, 63, v130
	v_readlane_b32 s4, v255, 10
	v_lshlrev_b32_e32 v96, 5, v64
	v_readlane_b32 s6, v255, 12
	v_readlane_b32 s7, v255, 13
	s_mov_b64 s[0:1], 0x1000
	v_ashrrev_i32_e32 v171, 6, v130
	v_lshl_add_u64 v[24:25], s[6:7], 0, v[96:97]
	v_lshl_add_u64 v[32:33], v[24:25], 0, s[0:1]
	s_mov_b64 s[0:1], 0x1800
	v_lshl_add_u64 v[36:37], v[24:25], 0, s[0:1]
	s_movk_i32 s0, 0x1000
	v_add_co_u32_e32 v28, vcc, s0, v24
	v_readlane_b32 s3, v254, 34
	s_nop 0
	v_addc_co_u32_e32 v29, vcc, 0, v25, vcc
	v_add_u32_e32 v48, s3, v171
	s_movk_i32 s0, 0x2000
	v_readlane_b32 s36, v251, 47
	v_cmp_gt_i32_e32 vcc, s0, v48
	v_mov_b32_e32 v49, 0x7ff
	v_mov_b32_e32 v50, 0xff
	v_readlane_b32 s37, v251, 48
	v_lshlrev_b32_e32 v0, 3, v130
	v_readlane_b32 s5, v255, 11
	v_readlane_b32 s8, v255, 14
	v_readlane_b32 s9, v255, 15
	v_readlane_b32 s10, v255, 16
	v_readlane_b32 s11, v255, 17
	v_readlane_b32 s12, v255, 18
	v_readlane_b32 s13, v255, 19
	v_readlane_b32 s14, v255, 20
	v_readlane_b32 s15, v255, 21
	v_readlane_b32 s16, v255, 22
	v_readlane_b32 s17, v255, 23
	v_readlane_b32 s18, v255, 24
	v_readlane_b32 s19, v255, 25
	v_cndmask_b32_e32 v49, v49, v50, vcc
	v_mov_b64_e32 v[50:51], s[36:37]
	s_movk_i32 s0, 0xc00
	v_and_b32_e32 v62, 56, v0
	global_load_dwordx4 v[0:3], v96, s[8:9] offset:16
	global_load_dwordx4 v[4:7], v96, s[6:7] offset:16
	global_load_dwordx4 v[8:11], v96, s[8:9]
	global_load_dwordx4 v[12:15], v96, s[6:7]
	global_load_dwordx4 v[16:19], v96, s[6:7] offset:2064
	global_load_dwordx4 v[20:23], v96, s[6:7] offset:2048
	v_readlane_b32 s4, v255, 26
	v_mad_i64_i32 v[50:51], s[0:1], v48, s0, v[50:51]
	v_lshlrev_b32_e32 v60, 4, v64
	v_mov_b32_e32 v61, v97
	v_lshlrev_b32_e32 v63, 2, v62
	v_readlane_b32 s6, v255, 28
	v_readlane_b32 s7, v255, 29
	v_lshl_add_u64 v[50:51], v[50:51], 0, v[60:61]
	global_load_dwordx4 v[24:27], v[28:29], off
	s_nop 0
	global_load_dwordx4 v[28:31], v[28:29], off offset:2048
	s_nop 0
	global_load_dwordx4 v[32:35], v[32:33], off offset:16
	s_nop 0
	global_load_dwordx4 v[36:39], v[36:37], off offset:16
	v_readlane_b32 s5, v255, 27
	global_load_dwordx4 v[40:43], v63, s[6:7] offset:16
	s_nop 3
	global_load_dwordx4 v[44:47], v63, s[4:5] offset:16
	global_load_dwordx4 v[126:129], v[50:51], off
	global_load_dwordx4 v[114:117], v[50:51], off offset:1024
	global_load_dwordx4 v[98:101], v[50:51], off offset:2048
	v_mov_b32_e32 v50, 0x802
	v_bfrev_b32_e32 v51, 4.0
	v_and_b32_e32 v54, v49, v48
	v_cndmask_b32_e32 v55, v50, v51, vcc
	v_cmp_lt_u32_e32 vcc, 1, v54
	v_cmp_lt_u32_e64 s[0:1], v54, v55
	v_add_u32_e32 v50, -2, v48
	s_and_b64 vcc, vcc, s[0:1]
	v_add_u32_e32 v52, 1, v54
	v_cndmask_b32_e32 v50, v48, v50, vcc
	v_cmp_ne_u32_e32 vcc, 0, v54
	v_cmp_lt_u32_e64 s[0:1], v52, v55
	s_and_b64 vcc, vcc, s[0:1]
	v_subbrev_co_u32_e32 v52, vcc, 0, v48, vcc
	v_add_u32_e32 v54, 3, v54
	v_mov_b32_e32 v56, s3
	v_cmp_lt_u32_e32 vcc, v54, v55
	v_ashrrev_i32_e32 v49, 31, v48
	v_ashrrev_i32_e32 v51, 31, v50
	v_addc_co_u32_e32 v54, vcc, v171, v56, vcc
	v_readlane_b32 s30, v251, 43
	v_ashrrev_i32_e32 v53, 31, v52
	v_ashrrev_i32_e32 v55, 31, v54
	v_lshlrev_b64 v[50:51], 10, v[50:51]
	v_readlane_b32 s31, v251, 44
	v_lshlrev_b64 v[52:53], 10, v[52:53]
	v_lshlrev_b64 v[48:49], 10, v[48:49]
	v_lshlrev_b64 v[54:55], 10, v[54:55]
	v_lshl_add_u64 v[50:51], s[30:31], 0, v[50:51]
	v_lshl_add_u64 v[52:53], s[30:31], 0, v[52:53]
	v_lshl_add_u64 v[48:49], s[30:31], 0, v[48:49]
	v_lshl_add_u64 v[54:55], s[30:31], 0, v[54:55]
	v_lshl_add_u64 v[50:51], v[50:51], 0, v[60:61]
	v_lshl_add_u64 v[52:53], v[52:53], 0, v[60:61]
	v_lshl_add_u64 v[48:49], v[48:49], 0, v[60:61]
	v_lshl_add_u64 v[54:55], v[54:55], 0, v[60:61]
	global_load_dwordx4 v[56:59], v[54:55], off
	global_load_dwordx4 v[92:95], v[52:53], off
	global_load_dwordx4 v[76:79], v[48:49], off
	global_load_dwordx4 v[102:105], v[50:51], off
	s_nop 0
	global_load_dwordx4 v[48:51], v63, s[6:7]
	global_load_dwordx4 v[52:55], v63, s[4:5]
	v_and_b32_e32 v63, 4, v130
	v_cmp_eq_u32_e64 s[0:1], 0, v63
	v_lshlrev_b32_e32 v63, 6, v130
	v_and_b32_e32 v63, 64, v63
	v_and_b32_e32 v66, 64, v210
	v_add_u32_e32 v176, 0, v63
	v_xor_b32_e32 v63, 1, v210
	v_add_u32_e32 v66, 64, v66
	v_cmp_lt_i32_e32 vcc, v63, v66
	v_lshl_add_u64 v[132:133], s[30:31], 0, v[60:61]
	v_readlane_b32 s30, v251, 24
	v_cndmask_b32_e32 v63, v210, v63, vcc
	v_lshlrev_b32_e32 v177, 2, v63
	v_xor_b32_e32 v63, 2, v210
	v_cmp_lt_i32_e32 vcc, v63, v66
	v_lshlrev_b32_e32 v62, 1, v62
	v_readlane_b32 s31, v251, 25
	v_cndmask_b32_e32 v63, v210, v63, vcc
	v_lshlrev_b32_e32 v178, 2, v63
	v_xor_b32_e32 v63, 4, v210
	v_cmp_lt_i32_e32 vcc, v63, v66
	v_lshl_add_u32 v65, v171, 1, 0
	v_lshl_add_u64 v[142:143], s[22:23], 0, v[60:61]
	v_cndmask_b32_e32 v63, v210, v63, vcc
	v_lshlrev_b32_e32 v179, 2, v63
	v_and_b32_e32 v63, 2, v130
	v_cmp_eq_u32_e64 s[40:41], 0, v63
	v_mov_b32_e32 v63, v97
	v_lshl_add_u64 v[134:135], s[30:31], 0, v[62:63]
	v_readlane_b32 s30, v252, 1
	v_readlane_b32 s31, v252, 2
	v_lshl_add_u64 v[144:145], s[36:37], 0, v[60:61]
	v_bfe_u32 v180, v130, 3, 3
	v_lshl_add_u64 v[136:137], s[30:31], 0, v[96:97]
	v_readlane_b32 s30, v251, 39
	v_readlane_b32 s31, v251, 40
	v_ashrrev_i32_e32 v131, 31, v130
	v_add_u32_e32 v181, s77, v171
	v_lshl_add_u64 v[138:139], s[30:31], 0, v[62:63]
	v_readlane_b32 s30, v252, 3
	v_lshlrev_b32_e32 v62, 7, v64
	v_lshlrev_b32_e32 v63, 4, v130
	v_readlane_b32 s31, v252, 4
	v_add_u32_e32 v182, v65, v62
	v_add_u32_e32 v183, 0, v63
	s_waitcnt vmcnt(8)
	v_mov_b64_e32 v[60:61], v[126:127]
	s_waitcnt vmcnt(7)
	v_mov_b64_e32 v[64:65], v[114:115]
	s_waitcnt vmcnt(6)
	v_mov_b64_e32 v[68:69], v[98:99]
	v_lshl_add_u64 v[140:141], s[30:31], 0, v[96:97]
	v_readlane_b32 s3, v254, 35
	s_mov_b32 s36, s34
	v_mov_b64_e32 v[62:63], v[128:129]
	v_mov_b64_e32 v[66:67], v[116:117]
	v_mov_b64_e32 v[70:71], v[100:101]
	v_readlane_b32 s8, v255, 30
	v_readlane_b32 s9, v255, 31
	v_readlane_b32 s10, v255, 32
	v_readlane_b32 s11, v255, 33
	v_readlane_b32 s12, v255, 34
	v_readlane_b32 s13, v255, 35
	v_readlane_b32 s14, v255, 36
	v_readlane_b32 s15, v255, 37
	v_readlane_b32 s16, v255, 38
	v_readlane_b32 s17, v255, 39
	v_readlane_b32 s18, v255, 40
	v_readlane_b32 s19, v255, 41
	s_waitcnt vmcnt(5)
	v_mov_b64_e32 v[90:91], v[58:59]
	s_waitcnt vmcnt(4)
	v_mov_b64_e32 v[84:85], v[92:93]
	s_waitcnt vmcnt(3)
	v_mov_b64_e32 v[82:83], v[78:79]
	s_waitcnt vmcnt(2)
	v_mov_b64_e32 v[72:73], v[102:103]
	v_mov_b64_e32 v[88:89], v[56:57]
	v_mov_b64_e32 v[80:81], v[76:77]
	v_mov_b64_e32 v[86:87], v[94:95]
	v_mov_b64_e32 v[74:75], v[104:105]
	s_waitcnt vmcnt(0)
	s_branch .LBB0_396
.LBB0_395:
	s_or_b64 exec, exec, s[46:47]
	v_lshlrev_b64 v[76:77], 10, v[146:147]
	v_cvt_pk_bf16_f32 v56, v98, v99
	v_cvt_pk_bf16_f32 v57, v100, v101
	v_cvt_pk_bf16_f32 v58, v106, v107
	v_cvt_pk_bf16_f32 v59, v110, v111
	v_lshl_add_u64 v[76:77], v[142:143], 0, v[76:77]
	global_store_dwordx4 v[76:77], v[56:59], off
	s_add_i32 s37, s3, 0x2000
	s_ashr_i32 s36, s36, 5
	v_mov_b32_e32 v56, 0x7f8
	v_mov_b32_e32 v57, 0xf8
	v_cndmask_b32_e32 v56, v57, v56, vcc
	v_and_b32_e32 v92, s37, v56
	s_ashr_i32 s37, s3, 11
	v_mov_b32_e32 v56, 0x800000
	v_cndmask_b32_e32 v96, 0, v56, vcc
	v_mov_b32_e32 v56, s36
	v_mov_b32_e32 v57, s37
	v_cndmask_b32_e32 v76, v56, v57, vcc
	v_ashrrev_i32_e32 v77, 31, v76
	s_waitcnt lgkmcnt(0)
	s_barrier
	ds_read_b128 v[56:59], v183
	v_readlane_b32 s36, v251, 26
	v_lshlrev_b64 v[76:77], 9, v[76:77]
	v_readlane_b32 s37, v251, 27
	v_lshl_add_u64 v[76:77], v[76:77], 0, v[130:131]
	v_lshlrev_b64 v[76:77], v108, v[76:77]
	v_lshl_add_u64 v[78:79], s[36:37], 0, v[96:97]
	v_lshl_add_u64 v[76:77], v[76:77], 1, v[78:79]
	v_lshlrev_b32_e32 v96, 1, v92
	v_lshl_add_u64 v[76:77], v[76:77], 0, v[96:97]
	s_waitcnt lgkmcnt(0)
	global_store_dwordx4 v[76:77], v[56:59], off
	s_waitcnt vmcnt(2)
	v_mov_b64_e32 v[104:105], v[74:75]
	v_mov_b64_e32 v[94:95], v[86:87]
	v_mov_b64_e32 v[76:77], v[80:81]
	v_mov_b64_e32 v[56:57], v[88:89]
	v_mov_b64_e32 v[128:129], v[62:63]
	v_mov_b64_e32 v[116:117], v[66:67]
	v_mov_b64_e32 v[100:101], v[70:71]
	s_add_i32 s3, s3, s77
	s_and_b64 vcc, exec, s[30:31]
	v_mov_b64_e32 v[102:103], v[72:73]
	v_mov_b64_e32 v[92:93], v[84:85]
	v_mov_b64_e32 v[78:79], v[82:83]
	v_mov_b64_e32 v[58:59], v[90:91]
	v_mov_b64_e32 v[126:127], v[60:61]
	v_mov_b64_e32 v[114:115], v[64:65]
	s_mov_b32 s36, s24
	v_mov_b64_e32 v[98:99], v[68:69]
	s_barrier
	s_cbranch_vccnz .LBB0_416

.LBB0_400:
	s_or_b64 exec, exec, s[46:47]
	v_lshlrev_b32_e32 v108, 16, v126
	v_and_b32_e32 v109, 0xffff0000, v126
	v_pk_mul_f32 v[150:151], v[108:109], v[108:109]
	v_lshlrev_b32_e32 v126, 16, v127
	v_and_b32_e32 v127, 0xffff0000, v127
	v_pk_mul_f32 v[152:153], v[126:127], v[126:127]
	v_add_f32_e32 v150, v150, v151
	v_lshlrev_b32_e32 v154, 16, v128
	v_and_b32_e32 v155, 0xffff0000, v128
	v_add_f32_e32 v150, v152, v150
	v_pk_mul_f32 v[156:157], v[154:155], v[154:155]
	v_add_f32_e32 v150, v153, v150
	v_lshlrev_b32_e32 v128, 16, v129
	v_and_b32_e32 v129, 0xffff0000, v129
	v_add_f32_e32 v150, v156, v150
	v_pk_mul_f32 v[158:159], v[128:129], v[128:129]
	v_add_f32_e32 v150, v157, v150
	v_add_f32_e32 v150, v158, v150
	v_add_f32_e32 v150, v159, v150
	ds_bpermute_b32 v151, v177, v150
	s_waitcnt lgkmcnt(0)
	v_add_f32_e32 v150, v150, v151
	ds_bpermute_b32 v151, v178, v150
	s_waitcnt lgkmcnt(0)
	v_add_f32_e32 v150, v150, v151
	ds_bpermute_b32 v151, v179, v150
	s_waitcnt lgkmcnt(0)
	v_add_f32_e32 v150, v150, v151
	v_fmamk_f32 v150, v150, 0x3c800000, v248
	v_mul_f32_e32 v151, 0x4b800000, v150
	v_cmp_gt_f32_e64 s[46:47], s82, v150
	s_nop 1
	v_cndmask_b32_e64 v150, v150, v151, s[46:47]
	v_rsq_f32_e32 v150, v150
	s_nop 0
	v_mul_f32_e32 v151, 0x45800000, v150
	v_cndmask_b32_e64 v156, v150, v151, s[46:47]
	v_pk_mul_f32 v[108:109], v[156:157], v[108:109] op_sel_hi:[0,1]
	v_pk_mul_f32 v[126:127], v[156:157], v[126:127] op_sel_hi:[0,1]
	v_pk_mul_f32 v[150:151], v[156:157], v[154:155] op_sel_hi:[0,1]
	v_pk_mul_f32 v[154:155], v[52:53], v[108:109]
	v_pk_mul_f32 v[108:109], v[156:157], v[128:129] op_sel_hi:[0,1]
	v_pk_mul_f32 v[152:153], v[54:55], v[126:127]
	v_pk_mul_f32 v[150:151], v[44:45], v[150:151]
	v_pk_mul_f32 v[128:129], v[46:47], v[108:109]
	ds_bpermute_b32 v156, v178, v154
	ds_bpermute_b32 v157, v178, v155
	ds_bpermute_b32 v158, v178, v152
	ds_bpermute_b32 v159, v178, v153
	ds_bpermute_b32 v160, v178, v150
	ds_bpermute_b32 v161, v178, v151
	ds_bpermute_b32 v174, v178, v128
	ds_bpermute_b32 v175, v178, v129
	v_mov_b64_e32 v[126:127], 0
	v_mov_b64_e32 v[108:109], 8
	s_and_saveexec_b64 s[46:47], vcc
	s_cbranch_execz .LBB0_402
	v_mov_b32_e32 v126, v111
	v_mov_b32_e32 v127, v113
	s_waitcnt lgkmcnt(4)
	v_pk_mul_f32 v[126:127], v[126:127], v[158:159]
	v_mov_b32_e32 v158, v123
	v_mov_b32_e32 v159, v125
	v_pk_mul_f32 v[108:109], v[148:149], v[156:157]
	v_mov_b32_e32 v156, v119
	v_mov_b32_e32 v157, v121
	s_waitcnt lgkmcnt(0)
	v_pk_mul_f32 v[158:159], v[158:159], v[174:175]
	v_pk_mul_f32 v[156:157], v[156:157], v[160:161]
	v_cndmask_b32_e64 v158, v158, -v158, s[40:41]
	v_cndmask_b32_e64 v159, v159, -v159, s[40:41]
	v_mov_b32_e32 v160, v122
	v_mov_b32_e32 v161, v124
	v_cndmask_b32_e64 v156, v156, -v156, s[40:41]
	v_cndmask_b32_e64 v157, v157, -v157, s[40:41]
	v_pk_fma_f32 v[128:129], v[160:161], v[128:129], v[158:159]
	v_mov_b32_e32 v158, v118
	v_mov_b32_e32 v159, v120
	v_cndmask_b32_e64 v127, v127, -v127, s[40:41]
	v_cndmask_b32_e64 v126, v126, -v126, s[40:41]
	v_cndmask_b32_e64 v109, v109, -v109, s[40:41]
	v_cndmask_b32_e64 v108, v108, -v108, s[40:41]
	v_pk_fma_f32 v[150:151], v[158:159], v[150:151], v[156:157]
	v_mov_b32_e32 v156, v110
	v_mov_b32_e32 v157, v112
	v_pk_fma_f32 v[152:153], v[156:157], v[152:153], v[126:127]
	v_pk_fma_f32 v[154:155], v[106:107], v[154:155], v[108:109]
	v_mov_b64_e32 v[126:127], 0x10000
	v_mov_b64_e32 v[108:109], 11
